# P2b gelu: IEEE division 2/(e+1) replaced by 2*v_rcp_f32 (1 ulp), f32 throughout
# speedup vs baseline: 1.0002x; 1.0002x over previous
.LBB0_712:
	v_and_b32_e32 v0, 0xf8, v157
	v_lshlrev_b32_e32 v128, 2, v0
	v_add_u32_e32 v0, s6, v164
	v_ashrrev_i32_e32 v1, 31, v0
	v_lshl_add_u64 v[20:21], s[82:83], 0, v[128:129]
	v_lshlrev_b64 v[2:3], 10, v[0:1]
	v_lshl_add_u64 v[2:3], v[20:21], 0, v[2:3]
	global_load_dwordx4 v[96:99], v[2:3], off offset:16
	global_load_dwordx4 v[104:107], v[2:3], off
	v_add_u32_e32 v2, 0x2000, v0
	v_ashrrev_i32_e32 v3, 31, v2
	v_lshlrev_b64 v[2:3], 10, v[2:3]
	v_lshl_add_u64 v[2:3], v[20:21], 0, v[2:3]
	global_load_dwordx4 v[100:103], v[2:3], off offset:16
	global_load_dwordx4 v[112:115], v[2:3], off
	v_add_u32_e32 v2, 0x4000, v0
	v_add_u32_e32 v0, 0x6000, v0
	v_ashrrev_i32_e32 v3, 31, v2
	v_ashrrev_i32_e32 v1, 31, v0
	v_lshlrev_b64 v[2:3], 10, v[2:3]
	v_lshlrev_b64 v[0:1], 10, v[0:1]
	v_lshl_add_u64 v[2:3], v[20:21], 0, v[2:3]
	v_lshl_add_u64 v[0:1], v[20:21], 0, v[0:1]
	global_load_dwordx4 v[108:111], v[2:3], off offset:16
	global_load_dwordx4 v[120:123], v[2:3], off
	global_load_dwordx4 v[116:119], v[0:1], off offset:16
	global_load_dwordx4 v[124:127], v[0:1], off
	v_add_u32_e32 v0, s6, v159
	v_ashrrev_i32_e32 v1, 31, v0
	v_lshlrev_b64 v[2:3], 10, v[0:1]
	v_lshl_add_u64 v[2:3], v[20:21], 0, v[2:3]
	global_load_dwordx4 v[64:67], v[2:3], off offset:16
	global_load_dwordx4 v[72:75], v[2:3], off
	v_add_u32_e32 v2, 0x2000, v0
	v_ashrrev_i32_e32 v3, 31, v2
	v_lshlrev_b64 v[2:3], 10, v[2:3]
	v_lshl_add_u64 v[2:3], v[20:21], 0, v[2:3]
	global_load_dwordx4 v[68:71], v[2:3], off offset:16
	global_load_dwordx4 v[80:83], v[2:3], off
	v_add_u32_e32 v2, 0x4000, v0
	v_add_u32_e32 v0, 0x6000, v0
	v_ashrrev_i32_e32 v3, 31, v2
	v_ashrrev_i32_e32 v1, 31, v0
	v_lshlrev_b64 v[2:3], 10, v[2:3]
	v_lshlrev_b64 v[0:1], 10, v[0:1]
	v_lshl_add_u64 v[2:3], v[20:21], 0, v[2:3]
	v_lshl_add_u64 v[0:1], v[20:21], 0, v[0:1]
	global_load_dwordx4 v[76:79], v[2:3], off offset:16
	global_load_dwordx4 v[88:91], v[2:3], off
	global_load_dwordx4 v[84:87], v[0:1], off offset:16
	global_load_dwordx4 v[92:95], v[0:1], off
	v_add_u32_e32 v0, s6, v162
	v_ashrrev_i32_e32 v1, 31, v0
	v_lshlrev_b64 v[2:3], 10, v[0:1]
	v_lshl_add_u64 v[2:3], v[20:21], 0, v[2:3]
	global_load_dwordx4 v[32:35], v[2:3], off offset:16
	global_load_dwordx4 v[40:43], v[2:3], off
	v_add_u32_e32 v2, 0x2000, v0
	v_ashrrev_i32_e32 v3, 31, v2
	v_lshlrev_b64 v[2:3], 10, v[2:3]
	v_lshl_add_u64 v[2:3], v[20:21], 0, v[2:3]
	global_load_dwordx4 v[36:39], v[2:3], off offset:16
	global_load_dwordx4 v[48:51], v[2:3], off
	v_add_u32_e32 v2, 0x4000, v0
	v_add_u32_e32 v0, 0x6000, v0
	v_ashrrev_i32_e32 v3, 31, v2
	v_ashrrev_i32_e32 v1, 31, v0
	v_lshlrev_b64 v[2:3], 10, v[2:3]
	v_lshlrev_b64 v[0:1], 10, v[0:1]
	v_add_u32_e32 v22, s6, v163
	v_lshl_add_u64 v[2:3], v[20:21], 0, v[2:3]
	v_lshl_add_u64 v[0:1], v[20:21], 0, v[0:1]
	v_ashrrev_i32_e32 v23, 31, v22
	global_load_dwordx4 v[44:47], v[2:3], off offset:16
	global_load_dwordx4 v[56:59], v[2:3], off
	global_load_dwordx4 v[52:55], v[0:1], off offset:16
	global_load_dwordx4 v[60:63], v[0:1], off
	v_lshlrev_b64 v[0:1], 10, v[22:23]
	v_lshl_add_u64 v[4:5], v[20:21], 0, v[0:1]
	global_load_dwordx4 v[0:3], v[4:5], off offset:16
	global_load_dwordx4 v[8:11], v[4:5], off
	v_add_u32_e32 v4, 0x2000, v22
	v_ashrrev_i32_e32 v5, 31, v4
	v_lshlrev_b64 v[4:5], 10, v[4:5]
	v_lshl_add_u64 v[12:13], v[20:21], 0, v[4:5]
	global_load_dwordx4 v[4:7], v[12:13], off offset:16
	global_load_dwordx4 v[16:19], v[12:13], off
	v_add_u32_e32 v12, 0x4000, v22
	v_add_u32_e32 v22, 0x6000, v22
	v_ashrrev_i32_e32 v13, 31, v12
	v_ashrrev_i32_e32 v23, 31, v22
	v_lshlrev_b64 v[12:13], 10, v[12:13]
	v_lshlrev_b64 v[22:23], 10, v[22:23]
	v_lshl_add_u64 v[24:25], v[20:21], 0, v[12:13]
	v_lshl_add_u64 v[28:29], v[20:21], 0, v[22:23]
	global_load_dwordx4 v[12:15], v[24:25], off offset:16
	s_nop 0
	global_load_dwordx4 v[24:27], v[24:25], off
	s_nop 0
	global_load_dwordx4 v[20:23], v[28:29], off offset:16
	s_nop 0
	global_load_dwordx4 v[28:31], v[28:29], off
	s_nop 0
	global_load_dwordx4 v[166:169], v[142:143], off offset:16
	global_load_dwordx4 v[170:173], v[142:143], off
	v_add_u32_e32 v158, 0x800, v158
	s_movk_i32 s3, 0x17ff
	v_add_u32_e32 v164, 64, v164
	v_add_u32_e32 v163, 64, v163
	v_add_u32_e32 v162, 64, v162
	v_add_u32_e32 v159, 64, v159
	v_add_u32_e32 v157, 0x4000, v157
	s_waitcnt vmcnt(1)
	v_pk_add_f32 v[96:97], v[166:167], v[96:97]
	s_nop 0
	v_pk_add_f32 v[96:97], v[96:97], v[100:101]
	s_waitcnt vmcnt(0)
	v_pk_add_f32 v[104:105], v[170:171], v[104:105]
	v_pk_add_f32 v[96:97], v[96:97], v[108:109]
	v_pk_add_f32 v[98:99], v[168:169], v[98:99]
	v_pk_add_f32 v[104:105], v[104:105], v[112:113]
	v_pk_add_f32 v[96:97], v[96:97], v[116:117]
	v_pk_add_f32 v[98:99], v[98:99], v[102:103]
	v_pk_add_f32 v[102:103], v[104:105], v[120:121]
	v_mul_f32_e32 v105, 0x3d372713, v96
	v_mul_f32_e32 v105, v96, v105
	v_fma_f32 v105, v96, v105, v96
	v_mul_f32_e32 v105, 0x3f4c422a, v105
	v_pk_add_f32 v[106:107], v[172:173], v[106:107]
	v_add_f32_e32 v105, v105, v105
	v_pk_add_f32 v[106:107], v[106:107], v[114:115]
	v_pk_add_f32 v[102:103], v[102:103], v[124:125]
	v_mul_f32_e32 v105, 0x3fb8aa3b, v105
	v_pk_add_f32 v[100:101], v[106:107], v[122:123]
	v_mul_f32_e32 v104, 0x3d372713, v102
	v_exp_f32_e32 v106, v105
	v_mul_f32_e32 v105, 0x3d372713, v103
	v_mul_f32_e32 v104, v102, v104
	v_mul_f32_e32 v105, v103, v105
	v_fma_f32 v104, v102, v104, v102
	v_fma_f32 v105, v103, v105, v103
	v_mul_f32_e32 v104, 0x3f4c422a, v104
	v_mul_f32_e32 v105, 0x3f4c422a, v105
	v_add_f32_e32 v104, v104, v104
	v_add_f32_e32 v105, v105, v105
	v_mul_f32_e32 v104, 0x3fb8aa3b, v104
	v_mul_f32_e32 v105, 0x3fb8aa3b, v105
	v_exp_f32_e32 v104, v104
	v_exp_f32_e32 v105, v105
	v_pk_add_f32 v[98:99], v[98:99], v[110:111]
	v_pk_mul_f32 v[102:103], v[102:103], 0.5 op_sel_hi:[1,0]
	v_pk_add_f32 v[98:99], v[98:99], v[118:119]
	v_pk_add_f32 v[104:105], v[104:105], 1.0 op_sel_hi:[1,0]
	v_pk_add_f32 v[100:101], v[100:101], v[126:127]
	v_rcp_f32_e32 v108, v105
	s_nop 0
	v_add_f32_e32 v105, v108, v108
	v_rcp_f32_e32 v108, v104
	s_nop 0
	v_add_f32_e32 v104, v108, v108
	v_pk_add_f32 v[104:105], v[104:105], 1.0 op_sel_hi:[1,0] neg_lo:[1,0] neg_hi:[1,0]
	s_nop 0
	v_pk_add_f32 v[104:105], v[104:105], 1.0 op_sel_hi:[1,0]
	s_nop 0
	v_pk_mul_f32 v[102:103], v[102:103], v[104:105]
	v_mul_f32_e32 v104, 0x3d372713, v97
	v_mul_f32_e32 v104, v97, v104
	v_fma_f32 v104, v97, v104, v97
	v_mul_f32_e32 v104, 0x3f4c422a, v104
	v_add_f32_e32 v104, v104, v104
	v_mul_f32_e32 v104, 0x3fb8aa3b, v104
	v_exp_f32_e32 v107, v104
	v_pk_mul_f32 v[96:97], v[96:97], 0.5 op_sel_hi:[1,0]
	v_pk_add_f32 v[104:105], v[106:107], 1.0 op_sel_hi:[1,0]
	s_nop 0
	v_rcp_f32_e32 v107, v105
	s_nop 0
	v_add_f32_e32 v105, v107, v107
	v_rcp_f32_e32 v107, v104
	s_nop 0
	v_add_f32_e32 v104, v107, v107
	v_pk_add_f32 v[104:105], v[104:105], 1.0 op_sel_hi:[1,0] neg_lo:[1,0] neg_hi:[1,0]
	s_nop 0
	v_pk_add_f32 v[104:105], v[104:105], 1.0 op_sel_hi:[1,0]
	s_nop 0
	v_pk_mul_f32 v[104:105], v[96:97], v[104:105]
	v_mul_f32_e32 v97, 0x3d372713, v98
	v_mul_f32_e32 v97, v98, v97
	v_fma_f32 v97, v98, v97, v98
	v_mul_f32_e32 v97, 0x3f4c422a, v97
	v_add_f32_e32 v97, v97, v97
	v_mul_f32_e32 v97, 0x3fb8aa3b, v97
	v_mul_f32_e32 v96, 0x3d372713, v100
	v_exp_f32_e32 v106, v97
	v_mul_f32_e32 v97, 0x3d372713, v101
	v_mul_f32_e32 v96, v100, v96
	v_mul_f32_e32 v97, v101, v97
	v_fma_f32 v96, v100, v96, v100
	v_fma_f32 v97, v101, v97, v101
	v_mul_f32_e32 v96, 0x3f4c422a, v96
	v_mul_f32_e32 v97, 0x3f4c422a, v97
	v_add_f32_e32 v96, v96, v96
	v_add_f32_e32 v97, v97, v97
	v_mul_f32_e32 v96, 0x3fb8aa3b, v96
	v_mul_f32_e32 v97, 0x3fb8aa3b, v97
	v_exp_f32_e32 v96, v96
	v_exp_f32_e32 v97, v97
	v_pk_mul_f32 v[100:101], v[100:101], 0.5 op_sel_hi:[1,0]
	v_pk_add_f32 v[96:97], v[96:97], 1.0 op_sel_hi:[1,0]
	s_nop 0
	v_rcp_f32_e32 v108, v97
	s_nop 0
	v_add_f32_e32 v97, v108, v108
	v_rcp_f32_e32 v108, v96
	s_nop 0
	v_add_f32_e32 v96, v108, v108
	v_pk_add_f32 v[96:97], v[96:97], 1.0 op_sel_hi:[1,0] neg_lo:[1,0] neg_hi:[1,0]
	s_nop 0
	v_pk_add_f32 v[96:97], v[96:97], 1.0 op_sel_hi:[1,0]
	s_nop 0
	v_pk_mul_f32 v[100:101], v[100:101], v[96:97]
	v_mul_f32_e32 v96, 0x3d372713, v99
	v_mul_f32_e32 v96, v99, v96
	v_fma_f32 v96, v99, v96, v99
	v_mul_f32_e32 v96, 0x3f4c422a, v96
	v_add_f32_e32 v96, v96, v96
	v_mul_f32_e32 v96, 0x3fb8aa3b, v96
	v_exp_f32_e32 v107, v96
	v_pk_mul_f32 v[98:99], v[98:99], 0.5 op_sel_hi:[1,0]
	v_pk_add_f32 v[96:97], v[106:107], 1.0 op_sel_hi:[1,0]
	s_nop 0
	v_rcp_f32_e32 v107, v97
	s_nop 0
	v_add_f32_e32 v97, v107, v107
	v_rcp_f32_e32 v107, v96
	s_nop 0
	v_add_f32_e32 v96, v107, v107
	v_pk_add_f32 v[96:97], v[96:97], 1.0 op_sel_hi:[1,0] neg_lo:[1,0] neg_hi:[1,0]
	s_nop 0
	v_pk_add_f32 v[96:97], v[96:97], 1.0 op_sel_hi:[1,0]
	s_nop 0
	v_pk_mul_f32 v[106:107], v[98:99], v[96:97]
	v_cvt_pk_bf16_f32 v96, v102, v103
	v_cvt_pk_bf16_f32 v97, v100, v101
	v_cvt_pk_bf16_f32 v98, v104, v105
	v_cvt_pk_bf16_f32 v99, v106, v107
	v_lshl_add_u64 v[100:101], v[150:151], 0, v[132:133]
	global_store_dwordx4 v[100:101], v[96:99], off
	global_load_dwordx4 v[96:99], v[142:143], off offset:16
	s_nop 0
	global_load_dwordx4 v[100:103], v[142:143], off
	v_lshl_add_u64 v[150:151], v[150:151], 0, s[0:1]
	s_waitcnt vmcnt(1)
	v_pk_add_f32 v[64:65], v[96:97], v[64:65]
	s_nop 0
	v_pk_add_f32 v[64:65], v[64:65], v[68:69]
	s_waitcnt vmcnt(0)
	v_pk_add_f32 v[72:73], v[100:101], v[72:73]
	v_pk_add_f32 v[64:65], v[64:65], v[76:77]
	v_pk_add_f32 v[66:67], v[98:99], v[66:67]
	v_pk_add_f32 v[72:73], v[72:73], v[80:81]
	v_pk_add_f32 v[64:65], v[64:65], v[84:85]
	v_pk_add_f32 v[66:67], v[66:67], v[70:71]
	v_pk_add_f32 v[70:71], v[72:73], v[88:89]
	v_mul_f32_e32 v73, 0x3d372713, v64
	v_mul_f32_e32 v73, v64, v73
	v_fma_f32 v73, v64, v73, v64
	v_mul_f32_e32 v73, 0x3f4c422a, v73
	v_pk_add_f32 v[74:75], v[102:103], v[74:75]
	v_add_f32_e32 v73, v73, v73
	v_pk_add_f32 v[74:75], v[74:75], v[82:83]
	v_pk_add_f32 v[70:71], v[70:71], v[92:93]
	v_mul_f32_e32 v73, 0x3fb8aa3b, v73
	v_pk_add_f32 v[68:69], v[74:75], v[90:91]
	v_mul_f32_e32 v72, 0x3d372713, v70
	v_exp_f32_e32 v74, v73
	v_mul_f32_e32 v73, 0x3d372713, v71
	v_mul_f32_e32 v72, v70, v72
	v_mul_f32_e32 v73, v71, v73
	v_fma_f32 v72, v70, v72, v70
	v_fma_f32 v73, v71, v73, v71
	v_mul_f32_e32 v72, 0x3f4c422a, v72
	v_mul_f32_e32 v73, 0x3f4c422a, v73
	v_add_f32_e32 v72, v72, v72
	v_add_f32_e32 v73, v73, v73
	v_mul_f32_e32 v72, 0x3fb8aa3b, v72
	v_mul_f32_e32 v73, 0x3fb8aa3b, v73
	v_exp_f32_e32 v72, v72
	v_exp_f32_e32 v73, v73
	v_pk_add_f32 v[66:67], v[66:67], v[78:79]
	v_pk_mul_f32 v[70:71], v[70:71], 0.5 op_sel_hi:[1,0]
	v_pk_add_f32 v[66:67], v[66:67], v[86:87]
	v_pk_add_f32 v[72:73], v[72:73], 1.0 op_sel_hi:[1,0]
	v_pk_add_f32 v[68:69], v[68:69], v[94:95]
	v_rcp_f32_e32 v76, v73
	s_nop 0
	v_add_f32_e32 v73, v76, v76
	v_rcp_f32_e32 v76, v72
	s_nop 0
	v_add_f32_e32 v72, v76, v76
	v_pk_add_f32 v[72:73], v[72:73], 1.0 op_sel_hi:[1,0] neg_lo:[1,0] neg_hi:[1,0]
	s_nop 0
	v_pk_add_f32 v[72:73], v[72:73], 1.0 op_sel_hi:[1,0]
	s_nop 0
	v_pk_mul_f32 v[70:71], v[70:71], v[72:73]
	v_mul_f32_e32 v72, 0x3d372713, v65
	v_mul_f32_e32 v72, v65, v72
	v_fma_f32 v72, v65, v72, v65
	v_mul_f32_e32 v72, 0x3f4c422a, v72
	v_add_f32_e32 v72, v72, v72
	v_mul_f32_e32 v72, 0x3fb8aa3b, v72
	v_exp_f32_e32 v75, v72
	v_pk_mul_f32 v[64:65], v[64:65], 0.5 op_sel_hi:[1,0]
	v_pk_add_f32 v[72:73], v[74:75], 1.0 op_sel_hi:[1,0]
	s_nop 0
	v_rcp_f32_e32 v75, v73
	s_nop 0
	v_add_f32_e32 v73, v75, v75
	v_rcp_f32_e32 v75, v72
	s_nop 0
	v_add_f32_e32 v72, v75, v75
	v_pk_add_f32 v[72:73], v[72:73], 1.0 op_sel_hi:[1,0] neg_lo:[1,0] neg_hi:[1,0]
	s_nop 0
	v_pk_add_f32 v[72:73], v[72:73], 1.0 op_sel_hi:[1,0]
	s_nop 0
	v_pk_mul_f32 v[72:73], v[64:65], v[72:73]
	v_mul_f32_e32 v65, 0x3d372713, v66
	v_mul_f32_e32 v65, v66, v65
	v_fma_f32 v65, v66, v65, v66
	v_mul_f32_e32 v65, 0x3f4c422a, v65
	v_add_f32_e32 v65, v65, v65
	v_mul_f32_e32 v65, 0x3fb8aa3b, v65
	v_mul_f32_e32 v64, 0x3d372713, v68
	v_exp_f32_e32 v74, v65
	v_mul_f32_e32 v65, 0x3d372713, v69
	v_mul_f32_e32 v64, v68, v64
	v_mul_f32_e32 v65, v69, v65
	v_fma_f32 v64, v68, v64, v68
	v_fma_f32 v65, v69, v65, v69
	v_mul_f32_e32 v64, 0x3f4c422a, v64
	v_mul_f32_e32 v65, 0x3f4c422a, v65
	v_add_f32_e32 v64, v64, v64
	v_add_f32_e32 v65, v65, v65
	v_mul_f32_e32 v64, 0x3fb8aa3b, v64
	v_mul_f32_e32 v65, 0x3fb8aa3b, v65
	v_exp_f32_e32 v64, v64
	v_exp_f32_e32 v65, v65
	v_pk_mul_f32 v[68:69], v[68:69], 0.5 op_sel_hi:[1,0]
	v_pk_add_f32 v[64:65], v[64:65], 1.0 op_sel_hi:[1,0]
	s_nop 0
	v_rcp_f32_e32 v76, v65
	s_nop 0
	v_add_f32_e32 v65, v76, v76
	v_rcp_f32_e32 v76, v64
	s_nop 0
	v_add_f32_e32 v64, v76, v76
	v_pk_add_f32 v[64:65], v[64:65], 1.0 op_sel_hi:[1,0] neg_lo:[1,0] neg_hi:[1,0]
	s_nop 0
	v_pk_add_f32 v[64:65], v[64:65], 1.0 op_sel_hi:[1,0]
	s_nop 0
	v_pk_mul_f32 v[68:69], v[68:69], v[64:65]
	v_mul_f32_e32 v64, 0x3d372713, v67
	v_mul_f32_e32 v64, v67, v64
	v_fma_f32 v64, v67, v64, v67
	v_mul_f32_e32 v64, 0x3f4c422a, v64
	v_add_f32_e32 v64, v64, v64
	v_mul_f32_e32 v64, 0x3fb8aa3b, v64
	v_exp_f32_e32 v75, v64
	v_pk_mul_f32 v[66:67], v[66:67], 0.5 op_sel_hi:[1,0]
	v_pk_add_f32 v[64:65], v[74:75], 1.0 op_sel_hi:[1,0]
	s_nop 0
	v_rcp_f32_e32 v75, v65
	s_nop 0
	v_add_f32_e32 v65, v75, v75
	v_rcp_f32_e32 v75, v64
	s_nop 0
	v_add_f32_e32 v64, v75, v75
	v_pk_add_f32 v[64:65], v[64:65], 1.0 op_sel_hi:[1,0] neg_lo:[1,0] neg_hi:[1,0]
	s_nop 0
	v_pk_add_f32 v[64:65], v[64:65], 1.0 op_sel_hi:[1,0]
	s_nop 0
	v_pk_mul_f32 v[74:75], v[66:67], v[64:65]
	v_cvt_pk_bf16_f32 v64, v70, v71
	v_cvt_pk_bf16_f32 v65, v68, v69
	v_cvt_pk_bf16_f32 v66, v72, v73
	v_cvt_pk_bf16_f32 v67, v74, v75
	v_lshl_add_u64 v[68:69], v[144:145], 0, v[132:133]
	global_store_dwordx4 v[68:69], v[64:67], off
	global_load_dwordx4 v[64:67], v[142:143], off offset:16
	s_nop 0
	global_load_dwordx4 v[68:71], v[142:143], off
	v_lshl_add_u64 v[144:145], v[144:145], 0, s[0:1]
	s_waitcnt vmcnt(1)
	v_pk_add_f32 v[32:33], v[64:65], v[32:33]
	s_nop 0
	v_pk_add_f32 v[32:33], v[32:33], v[36:37]
	s_waitcnt vmcnt(0)
	v_pk_add_f32 v[40:41], v[68:69], v[40:41]
	v_pk_add_f32 v[32:33], v[32:33], v[44:45]
	v_pk_add_f32 v[34:35], v[66:67], v[34:35]
	v_pk_add_f32 v[40:41], v[40:41], v[48:49]
	v_pk_add_f32 v[32:33], v[32:33], v[52:53]
	v_pk_add_f32 v[34:35], v[34:35], v[38:39]
	v_pk_add_f32 v[38:39], v[40:41], v[56:57]
	v_mul_f32_e32 v41, 0x3d372713, v32
	v_mul_f32_e32 v41, v32, v41
	v_fma_f32 v41, v32, v41, v32
	v_mul_f32_e32 v41, 0x3f4c422a, v41
	v_pk_add_f32 v[42:43], v[70:71], v[42:43]
	v_add_f32_e32 v41, v41, v41
	v_pk_add_f32 v[42:43], v[42:43], v[50:51]
	v_pk_add_f32 v[38:39], v[38:39], v[60:61]
	v_mul_f32_e32 v41, 0x3fb8aa3b, v41
	v_pk_add_f32 v[36:37], v[42:43], v[58:59]
	v_mul_f32_e32 v40, 0x3d372713, v38
	v_exp_f32_e32 v42, v41
	v_mul_f32_e32 v41, 0x3d372713, v39
	v_mul_f32_e32 v40, v38, v40
	v_mul_f32_e32 v41, v39, v41
	v_fma_f32 v40, v38, v40, v38
	v_fma_f32 v41, v39, v41, v39
	v_mul_f32_e32 v40, 0x3f4c422a, v40
	v_mul_f32_e32 v41, 0x3f4c422a, v41
	v_add_f32_e32 v40, v40, v40
	v_add_f32_e32 v41, v41, v41
	v_mul_f32_e32 v40, 0x3fb8aa3b, v40
	v_mul_f32_e32 v41, 0x3fb8aa3b, v41
	v_exp_f32_e32 v40, v40
	v_exp_f32_e32 v41, v41
	v_pk_add_f32 v[34:35], v[34:35], v[46:47]
	v_pk_mul_f32 v[38:39], v[38:39], 0.5 op_sel_hi:[1,0]
	v_pk_add_f32 v[34:35], v[34:35], v[54:55]
	v_pk_add_f32 v[40:41], v[40:41], 1.0 op_sel_hi:[1,0]
	v_pk_add_f32 v[36:37], v[36:37], v[62:63]
	v_rcp_f32_e32 v44, v41
	s_nop 0
	v_add_f32_e32 v41, v44, v44
	v_rcp_f32_e32 v44, v40
	s_nop 0
	v_add_f32_e32 v40, v44, v44
	v_pk_add_f32 v[40:41], v[40:41], 1.0 op_sel_hi:[1,0] neg_lo:[1,0] neg_hi:[1,0]
	s_nop 0
	v_pk_add_f32 v[40:41], v[40:41], 1.0 op_sel_hi:[1,0]
	s_nop 0
	v_pk_mul_f32 v[38:39], v[38:39], v[40:41]
	v_mul_f32_e32 v40, 0x3d372713, v33
	v_mul_f32_e32 v40, v33, v40
	v_fma_f32 v40, v33, v40, v33
	v_mul_f32_e32 v40, 0x3f4c422a, v40
	v_add_f32_e32 v40, v40, v40
	v_mul_f32_e32 v40, 0x3fb8aa3b, v40
	v_exp_f32_e32 v43, v40
	v_pk_mul_f32 v[32:33], v[32:33], 0.5 op_sel_hi:[1,0]
	v_pk_add_f32 v[40:41], v[42:43], 1.0 op_sel_hi:[1,0]
	s_nop 0
	v_rcp_f32_e32 v43, v41
	s_nop 0
	v_add_f32_e32 v41, v43, v43
	v_rcp_f32_e32 v43, v40
	s_nop 0
	v_add_f32_e32 v40, v43, v43
	v_pk_add_f32 v[40:41], v[40:41], 1.0 op_sel_hi:[1,0] neg_lo:[1,0] neg_hi:[1,0]
	s_nop 0
	v_pk_add_f32 v[40:41], v[40:41], 1.0 op_sel_hi:[1,0]
	s_nop 0
	v_pk_mul_f32 v[40:41], v[32:33], v[40:41]
	v_mul_f32_e32 v33, 0x3d372713, v34
	v_mul_f32_e32 v33, v34, v33
	v_fma_f32 v33, v34, v33, v34
	v_mul_f32_e32 v33, 0x3f4c422a, v33
	v_add_f32_e32 v33, v33, v33
	v_mul_f32_e32 v33, 0x3fb8aa3b, v33
	v_mul_f32_e32 v32, 0x3d372713, v36
	v_exp_f32_e32 v42, v33
	v_mul_f32_e32 v33, 0x3d372713, v37
	v_mul_f32_e32 v32, v36, v32
	v_mul_f32_e32 v33, v37, v33
	v_fma_f32 v32, v36, v32, v36
	v_fma_f32 v33, v37, v33, v37
	v_mul_f32_e32 v32, 0x3f4c422a, v32
	v_mul_f32_e32 v33, 0x3f4c422a, v33
	v_add_f32_e32 v32, v32, v32
	v_add_f32_e32 v33, v33, v33
	v_mul_f32_e32 v32, 0x3fb8aa3b, v32
	v_mul_f32_e32 v33, 0x3fb8aa3b, v33
	v_exp_f32_e32 v32, v32
	v_exp_f32_e32 v33, v33
	v_pk_mul_f32 v[36:37], v[36:37], 0.5 op_sel_hi:[1,0]
	v_pk_add_f32 v[32:33], v[32:33], 1.0 op_sel_hi:[1,0]
	s_nop 0
	v_rcp_f32_e32 v44, v33
	s_nop 0
	v_add_f32_e32 v33, v44, v44
	v_rcp_f32_e32 v44, v32
	s_nop 0
	v_add_f32_e32 v32, v44, v44
	v_pk_add_f32 v[32:33], v[32:33], 1.0 op_sel_hi:[1,0] neg_lo:[1,0] neg_hi:[1,0]
	s_nop 0
	v_pk_add_f32 v[32:33], v[32:33], 1.0 op_sel_hi:[1,0]
	s_nop 0
	v_pk_mul_f32 v[36:37], v[36:37], v[32:33]
	v_mul_f32_e32 v32, 0x3d372713, v35
	v_mul_f32_e32 v32, v35, v32
	v_fma_f32 v32, v35, v32, v35
	v_mul_f32_e32 v32, 0x3f4c422a, v32
	v_add_f32_e32 v32, v32, v32
	v_mul_f32_e32 v32, 0x3fb8aa3b, v32
	v_exp_f32_e32 v43, v32
	v_pk_mul_f32 v[34:35], v[34:35], 0.5 op_sel_hi:[1,0]
	v_pk_add_f32 v[32:33], v[42:43], 1.0 op_sel_hi:[1,0]
	s_nop 0
	v_rcp_f32_e32 v43, v33
	s_nop 0
	v_add_f32_e32 v33, v43, v43
	v_rcp_f32_e32 v43, v32
	s_nop 0
	v_add_f32_e32 v32, v43, v43
	v_pk_add_f32 v[32:33], v[32:33], 1.0 op_sel_hi:[1,0] neg_lo:[1,0] neg_hi:[1,0]
	s_nop 0
	v_pk_add_f32 v[32:33], v[32:33], 1.0 op_sel_hi:[1,0]
	s_nop 0
	v_pk_mul_f32 v[42:43], v[34:35], v[32:33]
	v_cvt_pk_bf16_f32 v32, v38, v39
	v_cvt_pk_bf16_f32 v33, v36, v37
	v_cvt_pk_bf16_f32 v34, v40, v41
	v_cvt_pk_bf16_f32 v35, v42, v43
	v_lshl_add_u64 v[36:37], v[146:147], 0, v[132:133]
	global_store_dwordx4 v[36:37], v[32:35], off
	global_load_dwordx4 v[32:35], v[142:143], off offset:16
	s_nop 0
	global_load_dwordx4 v[36:39], v[142:143], off
	v_lshl_add_u64 v[146:147], v[146:147], 0, s[0:1]
	s_waitcnt vmcnt(1)
	v_pk_add_f32 v[0:1], v[32:33], v[0:1]
	s_nop 0
	v_pk_add_f32 v[0:1], v[0:1], v[4:5]
	s_waitcnt vmcnt(0)
	v_pk_add_f32 v[8:9], v[36:37], v[8:9]
	v_pk_add_f32 v[0:1], v[0:1], v[12:13]
	v_pk_add_f32 v[2:3], v[34:35], v[2:3]
	v_pk_add_f32 v[8:9], v[8:9], v[16:17]
	v_pk_add_f32 v[0:1], v[0:1], v[20:21]
	v_pk_add_f32 v[2:3], v[2:3], v[6:7]
	v_pk_add_f32 v[6:7], v[8:9], v[24:25]
	v_mul_f32_e32 v9, 0x3d372713, v0
	v_mul_f32_e32 v9, v0, v9
	v_fma_f32 v9, v0, v9, v0
	v_mul_f32_e32 v9, 0x3f4c422a, v9
	v_pk_add_f32 v[10:11], v[38:39], v[10:11]
	v_add_f32_e32 v9, v9, v9
	v_pk_add_f32 v[10:11], v[10:11], v[18:19]
	v_pk_add_f32 v[6:7], v[6:7], v[28:29]
	v_mul_f32_e32 v9, 0x3fb8aa3b, v9
	v_pk_add_f32 v[4:5], v[10:11], v[26:27]
	v_mul_f32_e32 v8, 0x3d372713, v6
	v_exp_f32_e32 v10, v9
	v_mul_f32_e32 v9, 0x3d372713, v7
	v_mul_f32_e32 v8, v6, v8
	v_mul_f32_e32 v9, v7, v9
	v_fma_f32 v8, v6, v8, v6
	v_fma_f32 v9, v7, v9, v7
	v_mul_f32_e32 v8, 0x3f4c422a, v8
	v_mul_f32_e32 v9, 0x3f4c422a, v9
	v_add_f32_e32 v8, v8, v8
	v_add_f32_e32 v9, v9, v9
	v_mul_f32_e32 v8, 0x3fb8aa3b, v8
	v_mul_f32_e32 v9, 0x3fb8aa3b, v9
	v_exp_f32_e32 v8, v8
	v_exp_f32_e32 v9, v9
	v_pk_add_f32 v[2:3], v[2:3], v[14:15]
	v_pk_mul_f32 v[6:7], v[6:7], 0.5 op_sel_hi:[1,0]
	v_pk_add_f32 v[2:3], v[2:3], v[22:23]
	v_pk_add_f32 v[8:9], v[8:9], 1.0 op_sel_hi:[1,0]
	v_pk_add_f32 v[4:5], v[4:5], v[30:31]
	v_rcp_f32_e32 v12, v9
	s_nop 0
	v_add_f32_e32 v9, v12, v12
	v_rcp_f32_e32 v12, v8
	s_nop 0
	v_add_f32_e32 v8, v12, v12
	v_pk_add_f32 v[8:9], v[8:9], 1.0 op_sel_hi:[1,0] neg_lo:[1,0] neg_hi:[1,0]
	s_nop 0
	v_pk_add_f32 v[8:9], v[8:9], 1.0 op_sel_hi:[1,0]
	s_nop 0
	v_pk_mul_f32 v[6:7], v[6:7], v[8:9]
	v_mul_f32_e32 v8, 0x3d372713, v1
	v_mul_f32_e32 v8, v1, v8
	v_fma_f32 v8, v1, v8, v1
	v_mul_f32_e32 v8, 0x3f4c422a, v8
	v_add_f32_e32 v8, v8, v8
	v_mul_f32_e32 v8, 0x3fb8aa3b, v8
	v_exp_f32_e32 v11, v8
	v_pk_mul_f32 v[0:1], v[0:1], 0.5 op_sel_hi:[1,0]
	v_pk_add_f32 v[8:9], v[10:11], 1.0 op_sel_hi:[1,0]
	s_nop 0
	v_rcp_f32_e32 v11, v9
	s_nop 0
	v_add_f32_e32 v9, v11, v11
	v_rcp_f32_e32 v11, v8
	s_nop 0
	v_add_f32_e32 v8, v11, v11
	v_pk_add_f32 v[8:9], v[8:9], 1.0 op_sel_hi:[1,0] neg_lo:[1,0] neg_hi:[1,0]
	s_nop 0
	v_pk_add_f32 v[8:9], v[8:9], 1.0 op_sel_hi:[1,0]
	s_nop 0
	v_pk_mul_f32 v[8:9], v[0:1], v[8:9]
	v_mul_f32_e32 v1, 0x3d372713, v2
	v_mul_f32_e32 v1, v2, v1
	v_fma_f32 v1, v2, v1, v2
	v_mul_f32_e32 v1, 0x3f4c422a, v1
	v_add_f32_e32 v1, v1, v1
	v_mul_f32_e32 v1, 0x3fb8aa3b, v1
	v_mul_f32_e32 v0, 0x3d372713, v4
	v_exp_f32_e32 v10, v1
	v_mul_f32_e32 v1, 0x3d372713, v5
	v_mul_f32_e32 v0, v4, v0
	v_mul_f32_e32 v1, v5, v1
	v_fma_f32 v0, v4, v0, v4
	v_fma_f32 v1, v5, v1, v5
	v_mul_f32_e32 v0, 0x3f4c422a, v0
	v_mul_f32_e32 v1, 0x3f4c422a, v1
	v_add_f32_e32 v0, v0, v0
	v_add_f32_e32 v1, v1, v1
	v_mul_f32_e32 v0, 0x3fb8aa3b, v0
	v_mul_f32_e32 v1, 0x3fb8aa3b, v1
	v_exp_f32_e32 v0, v0
	v_exp_f32_e32 v1, v1
	v_pk_mul_f32 v[4:5], v[4:5], 0.5 op_sel_hi:[1,0]
	v_pk_add_f32 v[0:1], v[0:1], 1.0 op_sel_hi:[1,0]
	s_nop 0
	v_rcp_f32_e32 v12, v1
	s_nop 0
	v_add_f32_e32 v1, v12, v12
	v_rcp_f32_e32 v12, v0
	s_nop 0
	v_add_f32_e32 v0, v12, v12
	v_pk_add_f32 v[0:1], v[0:1], 1.0 op_sel_hi:[1,0] neg_lo:[1,0] neg_hi:[1,0]
	s_nop 0
	v_pk_add_f32 v[0:1], v[0:1], 1.0 op_sel_hi:[1,0]
	s_nop 0
	v_pk_mul_f32 v[4:5], v[4:5], v[0:1]
	v_mul_f32_e32 v0, 0x3d372713, v3
	v_mul_f32_e32 v0, v3, v0
	v_fma_f32 v0, v3, v0, v3
	v_mul_f32_e32 v0, 0x3f4c422a, v0
	v_add_f32_e32 v0, v0, v0
	v_mul_f32_e32 v0, 0x3fb8aa3b, v0
	v_exp_f32_e32 v11, v0
	v_pk_mul_f32 v[2:3], v[2:3], 0.5 op_sel_hi:[1,0]
	v_pk_add_f32 v[0:1], v[10:11], 1.0 op_sel_hi:[1,0]
	s_nop 0
	v_rcp_f32_e32 v11, v1
	s_nop 0
	v_add_f32_e32 v1, v11, v11
	v_rcp_f32_e32 v11, v0
	s_nop 0
	v_add_f32_e32 v0, v11, v11
	v_pk_add_f32 v[0:1], v[0:1], 1.0 op_sel_hi:[1,0] neg_lo:[1,0] neg_hi:[1,0]
	v_cmp_lt_u32_e32 vcc, s3, v158
	v_pk_add_f32 v[0:1], v[0:1], 1.0 op_sel_hi:[1,0]
	s_or_b64 s[4:5], vcc, s[4:5]
	v_pk_mul_f32 v[10:11], v[2:3], v[0:1]
	v_cvt_pk_bf16_f32 v0, v6, v7
	v_cvt_pk_bf16_f32 v1, v4, v5
	v_cvt_pk_bf16_f32 v2, v8, v9
	v_cvt_pk_bf16_f32 v3, v10, v11
	v_lshl_add_u64 v[4:5], v[148:149], 0, v[132:133]
	v_lshl_add_u64 v[148:149], v[148:149], 0, s[0:1]
	global_store_dwordx4 v[4:5], v[0:3], off
	s_andn2_b64 exec, exec, s[4:5]
	s_cbranch_execnz .LBB0_712
	s_or_b64 exec, exec, s[4:5]
	s_add_i32 s8, s8, 1
	s_mov_b64 s[4:5], 0
	s_branch .LBB0_703
